# phase 10 GEMM epilogue stores marked nt (final LN phase streams them from memory anyway)
# baseline (speedup 1.0000x reference)
.LBB0_965:
	ds_read_b128 v[144:147], v193
	ds_read_b128 v[148:151], v193 offset:1024
	ds_read_b128 v[152:155], v193 offset:2048
	ds_read_b128 v[156:159], v193 offset:3072
	s_add_u32 s40, s38, 0xfff80080
	s_addc_u32 s41, s39, -1
	s_cmp_eq_u32 s67, 28
	s_cselect_b32 s43, s15, s41
	s_cselect_b32 s42, s63, s40
	s_cselect_b32 s41, s13, s66
	s_cselect_b32 s40, s64, s65
	v_lshl_add_u64 v[188:189], s[38:39], 0, v[136:137]
	s_add_i32 m0, s37, 0xc000
	ds_read_b128 v[160:163], v194
	ds_read_b128 v[164:167], v194 offset:1024
	ds_read_b128 v[168:171], v194 offset:2048
	ds_read_b128 v[172:175], v194 offset:3072
	ds_read_b128 v[176:179], v194 offset:4096
	ds_read_b128 v[180:183], v194 offset:5120
	ds_read_b128 v[184:187], v194 offset:6144
	ds_read_b128 v[196:199], v194 offset:7168
	global_load_lds_dwordx4 v[188:189], off
	v_lshl_add_u64 v[188:189], s[38:39], 0, v[138:139]
	s_add_i32 m0, s37, 0xe000
	s_nop 0
	global_load_lds_dwordx4 v[188:189], off
	s_waitcnt lgkmcnt(8)
	s_barrier
	s_waitcnt lgkmcnt(0)
	s_setprio 1
	s_waitcnt lgkmcnt(0)
	v_mfma_f32_16x16x32_bf16 v[124:127], v[144:147], v[160:163], v[124:127]
	v_mfma_f32_16x16x32_bf16 v[120:123], v[152:155], v[160:163], v[120:123]
	v_mfma_f32_16x16x32_bf16 v[116:119], v[144:147], v[168:171], v[116:119]
	v_mfma_f32_16x16x32_bf16 v[112:115], v[152:155], v[168:171], v[112:115]
	v_mfma_f32_16x16x32_bf16 v[108:111], v[144:147], v[176:179], v[108:111]
	v_mfma_f32_16x16x32_bf16 v[104:107], v[152:155], v[176:179], v[104:107]
	v_mfma_f32_16x16x32_bf16 v[100:103], v[144:147], v[184:187], v[100:103]
	v_mfma_f32_16x16x32_bf16 v[96:99], v[152:155], v[184:187], v[96:99]
	v_mfma_f32_16x16x32_bf16 v[124:127], v[148:151], v[164:167], v[124:127]
	v_mfma_f32_16x16x32_bf16 v[120:123], v[156:159], v[164:167], v[120:123]
	v_mfma_f32_16x16x32_bf16 v[116:119], v[148:151], v[172:175], v[116:119]
	v_mfma_f32_16x16x32_bf16 v[112:115], v[156:159], v[172:175], v[112:115]
	v_mfma_f32_16x16x32_bf16 v[108:111], v[148:151], v[180:183], v[108:111]
	v_mfma_f32_16x16x32_bf16 v[104:107], v[156:159], v[180:183], v[104:107]
	v_mfma_f32_16x16x32_bf16 v[100:103], v[148:151], v[196:199], v[100:103]
	v_mfma_f32_16x16x32_bf16 v[96:99], v[156:159], v[196:199], v[96:99]
	s_setprio 0
	s_barrier
	s_add_i32 s68, s59, s44
	v_lshl_add_u64 v[188:189], s[40:41], 0, v[130:131]
	s_mov_b32 m0, s68
	ds_read_b128 v[200:203], v195
	ds_read_b128 v[204:207], v195 offset:1024
	ds_read_b128 v[208:211], v195 offset:2048
	ds_read_b128 v[212:215], v195 offset:3072
	global_load_lds_dwordx4 v[188:189], off
	v_lshl_add_u64 v[216:217], s[40:41], 0, v[134:135]
	s_add_i32 m0, s68, 0x2000
	s_nop 0
	global_load_lds_dwordx4 v[216:217], off
	s_barrier
	s_waitcnt lgkmcnt(0)
	s_setprio 1
	s_waitcnt lgkmcnt(0)
	v_mfma_f32_16x16x32_bf16 v[60:63], v[200:203], v[160:163], v[60:63]
	v_mfma_f32_16x16x32_bf16 v[56:59], v[208:211], v[160:163], v[56:59]
	v_mfma_f32_16x16x32_bf16 v[52:55], v[200:203], v[168:171], v[52:55]
	v_mfma_f32_16x16x32_bf16 v[48:51], v[208:211], v[168:171], v[48:51]
	v_mfma_f32_16x16x32_bf16 v[44:47], v[200:203], v[176:179], v[44:47]
	v_mfma_f32_16x16x32_bf16 v[40:43], v[208:211], v[176:179], v[40:43]
	v_mfma_f32_16x16x32_bf16 v[36:39], v[200:203], v[184:187], v[36:39]
	v_mfma_f32_16x16x32_bf16 v[32:35], v[208:211], v[184:187], v[32:35]
	v_mfma_f32_16x16x32_bf16 v[60:63], v[204:207], v[164:167], v[60:63]
	v_mfma_f32_16x16x32_bf16 v[56:59], v[212:215], v[164:167], v[56:59]
	v_mfma_f32_16x16x32_bf16 v[52:55], v[204:207], v[172:175], v[52:55]
	v_mfma_f32_16x16x32_bf16 v[48:51], v[212:215], v[172:175], v[48:51]
	v_mfma_f32_16x16x32_bf16 v[44:47], v[204:207], v[180:183], v[44:47]
	v_mfma_f32_16x16x32_bf16 v[40:43], v[212:215], v[180:183], v[40:43]
	v_mfma_f32_16x16x32_bf16 v[36:39], v[204:207], v[196:199], v[36:39]
	v_mfma_f32_16x16x32_bf16 v[32:35], v[212:215], v[196:199], v[32:35]
	s_setprio 0
	s_mov_b32 m0, s37
	v_lshl_add_u64 v[218:219], s[42:43], 0, v[128:129]
	s_barrier
	ds_read_b128 v[160:163], v194 offset:16384
	ds_read_b128 v[164:167], v194 offset:17408
	ds_read_b128 v[168:171], v194 offset:18432
	ds_read_b128 v[172:175], v194 offset:19456
	ds_read_b128 v[176:179], v194 offset:20480
	ds_read_b128 v[180:183], v194 offset:21504
	ds_read_b128 v[184:187], v194 offset:22528
	ds_read_b128 v[196:199], v194 offset:23552
	global_load_lds_dwordx4 v[218:219], off
	v_lshl_add_u64 v[220:221], s[42:43], 0, v[132:133]
	s_mov_b32 m0, s45
	s_nop 0
	global_load_lds_dwordx4 v[220:221], off
	s_barrier
	s_waitcnt lgkmcnt(0)
	s_setprio 1
	s_waitcnt lgkmcnt(0)
	v_mfma_f32_16x16x32_bf16 v[92:95], v[144:147], v[160:163], v[92:95]
	v_mfma_f32_16x16x32_bf16 v[88:91], v[152:155], v[160:163], v[88:91]
	v_mfma_f32_16x16x32_bf16 v[84:87], v[144:147], v[168:171], v[84:87]
	v_mfma_f32_16x16x32_bf16 v[80:83], v[152:155], v[168:171], v[80:83]
	v_mfma_f32_16x16x32_bf16 v[76:79], v[144:147], v[176:179], v[76:79]
	v_mfma_f32_16x16x32_bf16 v[72:75], v[152:155], v[176:179], v[72:75]
	v_mfma_f32_16x16x32_bf16 v[68:71], v[144:147], v[184:187], v[68:71]
	v_mfma_f32_16x16x32_bf16 v[64:67], v[152:155], v[184:187], v[64:67]
	v_mfma_f32_16x16x32_bf16 v[92:95], v[148:151], v[164:167], v[92:95]
	v_mfma_f32_16x16x32_bf16 v[88:91], v[156:159], v[164:167], v[88:91]
	v_mfma_f32_16x16x32_bf16 v[84:87], v[148:151], v[172:175], v[84:87]
	v_mfma_f32_16x16x32_bf16 v[80:83], v[156:159], v[172:175], v[80:83]
	v_mfma_f32_16x16x32_bf16 v[76:79], v[148:151], v[180:183], v[76:79]
	v_mfma_f32_16x16x32_bf16 v[72:75], v[156:159], v[180:183], v[72:75]
	v_mfma_f32_16x16x32_bf16 v[68:71], v[148:151], v[196:199], v[68:71]
	v_mfma_f32_16x16x32_bf16 v[64:67], v[156:159], v[196:199], v[64:67]
	s_setprio 0
	s_barrier
	s_add_u32 s68, s40, 0x80000
	s_addc_u32 s69, s41, 0
	s_add_i32 s70, s60, s44
	v_lshl_add_u64 v[144:145], s[68:69], 0, v[130:131]
	s_mov_b32 m0, s70
	s_nop 0
	global_load_lds_dwordx4 v[144:145], off
	v_lshl_add_u64 v[144:145], s[68:69], 0, v[134:135]
	s_add_i32 m0, s70, 0x2000
	s_nop 0
	global_load_lds_dwordx4 v[144:145], off
	s_waitcnt vmcnt(6)
	s_barrier
	s_setprio 1
	v_mfma_f32_16x16x32_bf16 v[28:31], v[200:203], v[160:163], v[28:31]
	v_mfma_f32_16x16x32_bf16 v[24:27], v[208:211], v[160:163], v[24:27]
	v_mfma_f32_16x16x32_bf16 v[20:23], v[200:203], v[168:171], v[20:23]
	v_mfma_f32_16x16x32_bf16 v[16:19], v[208:211], v[168:171], v[16:19]
	v_mfma_f32_16x16x32_bf16 v[12:15], v[200:203], v[176:179], v[12:15]
	v_mfma_f32_16x16x32_bf16 v[8:11], v[208:211], v[176:179], v[8:11]
	v_mfma_f32_16x16x32_bf16 v[4:7], v[200:203], v[184:187], v[4:7]
	v_mfma_f32_16x16x32_bf16 v[0:3], v[208:211], v[184:187], v[0:3]
	v_mfma_f32_16x16x32_bf16 v[28:31], v[204:207], v[164:167], v[28:31]
	v_mfma_f32_16x16x32_bf16 v[24:27], v[212:215], v[164:167], v[24:27]
	v_mfma_f32_16x16x32_bf16 v[20:23], v[204:207], v[172:175], v[20:23]
	v_mfma_f32_16x16x32_bf16 v[16:19], v[212:215], v[172:175], v[16:19]
	v_mfma_f32_16x16x32_bf16 v[12:15], v[204:207], v[180:183], v[12:15]
	v_mfma_f32_16x16x32_bf16 v[8:11], v[212:215], v[180:183], v[8:11]
	v_mfma_f32_16x16x32_bf16 v[4:7], v[204:207], v[196:199], v[4:7]
	v_mfma_f32_16x16x32_bf16 v[0:3], v[212:215], v[196:199], v[0:3]
	s_setprio 0
	s_add_i32 s68, 0, 0x18000
	v_add_u32_e32 v156, s68, v192
	s_barrier
	ds_read_b128 v[144:147], v156
	ds_read_b128 v[148:151], v156 offset:1024
	ds_read_b128 v[152:155], v156 offset:2048
	ds_read_b128 v[156:159], v156 offset:3072
	s_add_u32 s42, s42, 0x80000
	s_addc_u32 s43, s43, 0
	s_mov_b32 m0, s50
	v_lshl_add_u64 v[200:201], s[42:43], 0, v[128:129]
	ds_read_b128 v[160:163], v194 offset:32768
	ds_read_b128 v[164:167], v194 offset:33792
	ds_read_b128 v[168:171], v194 offset:34816
	ds_read_b128 v[172:175], v194 offset:35840
	ds_read_b128 v[176:179], v194 offset:36864
	ds_read_b128 v[180:183], v194 offset:37888
	ds_read_b128 v[184:187], v194 offset:38912
	ds_read_b128 v[196:199], v194 offset:39936
	global_load_lds_dwordx4 v[200:201], off
	v_lshl_add_u64 v[200:201], s[42:43], 0, v[132:133]
	s_mov_b32 m0, s51
	s_nop 0
	global_load_lds_dwordx4 v[200:201], off
	s_waitcnt lgkmcnt(8)
	s_barrier
	s_waitcnt lgkmcnt(0)
	s_setprio 1
	s_waitcnt lgkmcnt(0)
	v_mfma_f32_16x16x32_bf16 v[124:127], v[144:147], v[160:163], v[124:127]
	v_mfma_f32_16x16x32_bf16 v[120:123], v[152:155], v[160:163], v[120:123]
	v_mfma_f32_16x16x32_bf16 v[116:119], v[144:147], v[168:171], v[116:119]
	v_mfma_f32_16x16x32_bf16 v[112:115], v[152:155], v[168:171], v[112:115]
	v_mfma_f32_16x16x32_bf16 v[108:111], v[144:147], v[176:179], v[108:111]
	v_mfma_f32_16x16x32_bf16 v[104:107], v[152:155], v[176:179], v[104:107]
	v_mfma_f32_16x16x32_bf16 v[100:103], v[144:147], v[184:187], v[100:103]
	v_mfma_f32_16x16x32_bf16 v[96:99], v[152:155], v[184:187], v[96:99]
	v_mfma_f32_16x16x32_bf16 v[124:127], v[148:151], v[164:167], v[124:127]
	v_mfma_f32_16x16x32_bf16 v[120:123], v[156:159], v[164:167], v[120:123]
	v_mfma_f32_16x16x32_bf16 v[116:119], v[148:151], v[172:175], v[116:119]
	v_mfma_f32_16x16x32_bf16 v[112:115], v[156:159], v[172:175], v[112:115]
	v_mfma_f32_16x16x32_bf16 v[108:111], v[148:151], v[180:183], v[108:111]
	v_mfma_f32_16x16x32_bf16 v[104:107], v[156:159], v[180:183], v[104:107]
	v_mfma_f32_16x16x32_bf16 v[100:103], v[148:151], v[196:199], v[100:103]
	v_mfma_f32_16x16x32_bf16 v[96:99], v[156:159], v[196:199], v[96:99]
	s_setprio 0
	s_barrier
	s_add_i32 s42, 0, 0x1c000
	s_add_i32 s43, s68, s44
	v_add_u32_e32 v190, s42, v192
	v_lshl_add_u64 v[188:189], v[188:189], 0, s[6:7]
	s_mov_b32 m0, s43
	ds_read_b128 v[200:203], v190
	ds_read_b128 v[204:207], v190 offset:1024
	ds_read_b128 v[208:211], v190 offset:2048
	ds_read_b128 v[212:215], v190 offset:3072
	global_load_lds_dwordx4 v[188:189], off
	v_lshl_add_u64 v[188:189], v[216:217], 0, s[6:7]
	s_add_i32 m0, s43, 0x2000
	s_nop 0
	global_load_lds_dwordx4 v[188:189], off
	s_barrier
	s_waitcnt lgkmcnt(0)
	s_setprio 1
	s_waitcnt lgkmcnt(0)
	v_mfma_f32_16x16x32_bf16 v[60:63], v[200:203], v[160:163], v[60:63]
	v_mfma_f32_16x16x32_bf16 v[56:59], v[208:211], v[160:163], v[56:59]
	v_mfma_f32_16x16x32_bf16 v[52:55], v[200:203], v[168:171], v[52:55]
	v_mfma_f32_16x16x32_bf16 v[48:51], v[208:211], v[168:171], v[48:51]
	v_mfma_f32_16x16x32_bf16 v[44:47], v[200:203], v[176:179], v[44:47]
	v_mfma_f32_16x16x32_bf16 v[40:43], v[208:211], v[176:179], v[40:43]
	v_mfma_f32_16x16x32_bf16 v[36:39], v[200:203], v[184:187], v[36:39]
	v_mfma_f32_16x16x32_bf16 v[32:35], v[208:211], v[184:187], v[32:35]
	v_mfma_f32_16x16x32_bf16 v[60:63], v[204:207], v[164:167], v[60:63]
	v_mfma_f32_16x16x32_bf16 v[56:59], v[212:215], v[164:167], v[56:59]
	v_mfma_f32_16x16x32_bf16 v[52:55], v[204:207], v[172:175], v[52:55]
	v_mfma_f32_16x16x32_bf16 v[48:51], v[212:215], v[172:175], v[48:51]
	v_mfma_f32_16x16x32_bf16 v[44:47], v[204:207], v[180:183], v[44:47]
	v_mfma_f32_16x16x32_bf16 v[40:43], v[212:215], v[180:183], v[40:43]
	v_mfma_f32_16x16x32_bf16 v[36:39], v[204:207], v[196:199], v[36:39]
	v_mfma_f32_16x16x32_bf16 v[32:35], v[212:215], v[196:199], v[32:35]
	s_setprio 0
	s_mov_b32 m0, s55
	v_lshl_add_u64 v[188:189], v[218:219], 0, s[6:7]
	s_barrier
	ds_read_b128 v[160:163], v194 offset:49152
	ds_read_b128 v[164:167], v194 offset:50176
	ds_read_b128 v[168:171], v194 offset:51200
	ds_read_b128 v[172:175], v194 offset:52224
	ds_read_b128 v[176:179], v194 offset:53248
	ds_read_b128 v[180:183], v194 offset:54272
	ds_read_b128 v[184:187], v194 offset:55296
	ds_read_b128 v[196:199], v194 offset:56320
	global_load_lds_dwordx4 v[188:189], off
	v_lshl_add_u64 v[188:189], v[220:221], 0, s[6:7]
	s_mov_b32 m0, s56
	s_nop 0
	global_load_lds_dwordx4 v[188:189], off
	s_barrier
	s_waitcnt lgkmcnt(0)
	s_setprio 1
	s_waitcnt lgkmcnt(0)
	v_mfma_f32_16x16x32_bf16 v[92:95], v[144:147], v[160:163], v[92:95]
	v_mfma_f32_16x16x32_bf16 v[88:91], v[152:155], v[160:163], v[88:91]
	v_mfma_f32_16x16x32_bf16 v[84:87], v[144:147], v[168:171], v[84:87]
	v_mfma_f32_16x16x32_bf16 v[80:83], v[152:155], v[168:171], v[80:83]
	v_mfma_f32_16x16x32_bf16 v[76:79], v[144:147], v[176:179], v[76:79]
	v_mfma_f32_16x16x32_bf16 v[72:75], v[152:155], v[176:179], v[72:75]
	v_mfma_f32_16x16x32_bf16 v[68:71], v[144:147], v[184:187], v[68:71]
	v_mfma_f32_16x16x32_bf16 v[64:67], v[152:155], v[184:187], v[64:67]
	v_mfma_f32_16x16x32_bf16 v[92:95], v[148:151], v[164:167], v[92:95]
	v_mfma_f32_16x16x32_bf16 v[88:91], v[156:159], v[164:167], v[88:91]
	v_mfma_f32_16x16x32_bf16 v[84:87], v[148:151], v[172:175], v[84:87]
	v_mfma_f32_16x16x32_bf16 v[80:83], v[156:159], v[172:175], v[80:83]
	v_mfma_f32_16x16x32_bf16 v[76:79], v[148:151], v[180:183], v[76:79]
	v_mfma_f32_16x16x32_bf16 v[72:75], v[156:159], v[180:183], v[72:75]
	v_mfma_f32_16x16x32_bf16 v[68:71], v[148:151], v[196:199], v[68:71]
	v_mfma_f32_16x16x32_bf16 v[64:67], v[156:159], v[196:199], v[64:67]
	s_setprio 0
	s_barrier
	s_add_u32 s40, s40, 0x80080
	s_addc_u32 s41, s41, 0
	s_add_i32 s42, s42, s44
	v_lshl_add_u64 v[144:145], s[40:41], 0, v[130:131]
	s_mov_b32 m0, s42
	s_nop 0
	global_load_lds_dwordx4 v[144:145], off
	v_lshl_add_u64 v[144:145], s[40:41], 0, v[134:135]
	s_add_i32 m0, s42, 0x2000
	s_nop 0
	global_load_lds_dwordx4 v[144:145], off
	s_waitcnt vmcnt(6)
	s_barrier
	s_setprio 1
	v_mfma_f32_16x16x32_bf16 v[28:31], v[200:203], v[160:163], v[28:31]
	v_mfma_f32_16x16x32_bf16 v[24:27], v[208:211], v[160:163], v[24:27]
	v_mfma_f32_16x16x32_bf16 v[20:23], v[200:203], v[168:171], v[20:23]
	v_mfma_f32_16x16x32_bf16 v[16:19], v[208:211], v[168:171], v[16:19]
	v_mfma_f32_16x16x32_bf16 v[12:15], v[200:203], v[176:179], v[12:15]
	v_mfma_f32_16x16x32_bf16 v[8:11], v[208:211], v[176:179], v[8:11]
	v_mfma_f32_16x16x32_bf16 v[4:7], v[200:203], v[184:187], v[4:7]
	v_mfma_f32_16x16x32_bf16 v[0:3], v[208:211], v[184:187], v[0:3]
	v_mfma_f32_16x16x32_bf16 v[28:31], v[204:207], v[164:167], v[28:31]
	v_mfma_f32_16x16x32_bf16 v[24:27], v[212:215], v[164:167], v[24:27]
	v_mfma_f32_16x16x32_bf16 v[20:23], v[204:207], v[172:175], v[20:23]
	v_mfma_f32_16x16x32_bf16 v[16:19], v[212:215], v[172:175], v[16:19]
	v_mfma_f32_16x16x32_bf16 v[12:15], v[204:207], v[180:183], v[12:15]
	v_mfma_f32_16x16x32_bf16 v[8:11], v[212:215], v[180:183], v[8:11]
	v_mfma_f32_16x16x32_bf16 v[4:7], v[204:207], v[196:199], v[4:7]
	v_mfma_f32_16x16x32_bf16 v[0:3], v[212:215], v[196:199], v[0:3]
	s_setprio 0
	s_add_i32 s67, s67, 2
	s_add_u32 s38, s38, 0x100
	s_addc_u32 s39, s39, 0
	s_add_u32 s65, s65, 0x100
	s_addc_u32 s66, s66, 0
	s_cmp_gt_u32 s67, 29
	s_barrier
	s_cbranch_scc0 .LBB0_965
	v_mov_b32_e32 v144, v254
	s_lshl_b32 s15, s36, 8
	v_readfirstlane_b32 s13, v144
	s_ashr_i32 s36, s13, 2
	s_andn2_b32 s36, s36, 63
	s_lshr_b32 s13, s13, 1
	s_add_i32 s36, s36, s15
	s_lshl_b32 s15, s62, 8
	s_and_b32 s13, s13, 0x60
	v_and_or_b32 v178, v144, 15, s36
	s_or_b32 s13, s13, s15
	v_lshrrev_b32_e32 v144, 1, v144
	v_and_or_b32 v144, v144, 24, s13
	v_ashrrev_i32_e32 v179, 31, v178
	v_lshlrev_b64 v[146:147], 12, v[178:179]
	v_ashrrev_i32_e32 v145, 31, v144
	s_ashr_i32 s13, s36, 12
	v_lshlrev_b64 v[188:189], 2, v[144:145]
	v_lshl_add_u64 v[146:147], s[26:27], 0, v[146:147]
	s_mul_i32 s38, s13, 0xc00
	v_lshl_add_u64 v[150:151], v[146:147], 0, v[188:189]
	s_ashr_i32 s39, s38, 31
	v_or_b32_e32 v146, 16, v178
	v_lshl_add_u64 v[154:155], s[46:47], 0, v[188:189]
	v_lshl_add_u64 v[156:157], s[48:49], 0, v[188:189]
	v_lshl_add_u64 v[144:145], v[178:179], 3, s[24:25]
	s_lshl_b64 s[38:39], s[38:39], 2
	v_ashrrev_i32_e32 v147, 31, v146
	global_load_dwordx4 v[168:171], v[154:155], off offset:16
	global_load_dwordx4 v[164:167], v[154:155], off
	global_load_dwordx4 v[180:183], v[156:157], off offset:16
	global_load_dwordx4 v[172:175], v[156:157], off
	global_load_dwordx2 v[224:225], v[144:145], off
	global_load_dwordx4 v[184:187], v[150:151], off offset:16
	global_load_dwordx4 v[196:199], v[150:151], off
	v_lshl_add_u64 v[158:159], v[146:147], 3, s[24:25]
	v_lshlrev_b64 v[146:147], 12, v[146:147]
	s_add_u32 s38, s53, s38
	v_lshl_add_u64 v[146:147], s[26:27], 0, v[146:147]
	s_addc_u32 s39, s54, s39
	v_lshl_add_u64 v[148:149], v[146:147], 0, v[188:189]
	v_lshl_add_u64 v[160:161], s[38:39], 0, v[188:189]
	global_load_dwordx2 v[226:227], v[158:159], off
	global_load_dwordx4 v[200:203], v[148:149], off
	global_load_dwordx4 v[204:207], v[160:161], off
	global_load_dwordx4 v[208:211], v[160:161], off offset:16
	global_load_dwordx4 v[212:215], v[148:149], off offset:16
	v_or_b32_e32 v146, 32, v178
	v_ashrrev_i32_e32 v147, 31, v146
	v_lshl_add_u64 v[152:153], v[146:147], 3, s[24:25]
	v_lshlrev_b64 v[146:147], 12, v[146:147]
	v_lshl_add_u64 v[146:147], s[26:27], 0, v[146:147]
	v_lshl_add_u64 v[146:147], v[146:147], 0, v[188:189]
	global_load_dwordx4 v[216:219], v[146:147], off offset:16
	global_load_dwordx4 v[220:223], v[146:147], off
	s_mov_b32 s62, s12
	s_mov_b32 s36, s14
	s_mov_b64 s[40:41], s[22:23]
	s_mov_b64 s[38:39], s[16:17]
	s_waitcnt vmcnt(0)
	v_pk_mul_f32 v[168:169], v[168:169], s[8:9] op_sel_hi:[1,0]
	v_pk_mul_f32 v[162:163], v[166:167], s[8:9] op_sel_hi:[1,0]
	v_pk_mul_f32 v[166:167], v[164:165], s[8:9] op_sel_hi:[1,0]
	v_pk_mul_f32 v[164:165], v[170:171], s[8:9] op_sel_hi:[1,0]
	v_pk_mul_f32 v[170:171], v[174:175], s[8:9] op_sel_hi:[1,0]
	v_pk_mul_f32 v[174:175], v[172:173], s[8:9] op_sel_hi:[1,0]
	v_pk_mul_f32 v[172:173], v[182:183], s[8:9] op_sel_hi:[1,0]
	v_pk_mul_f32 v[176:177], v[180:181], s[8:9] op_sel_hi:[1,0]
	v_sub_f32_e32 v181, v197, v224
	v_sub_f32_e32 v180, v196, v224
	v_sub_f32_e32 v183, v199, v224
	v_sub_f32_e32 v182, v198, v224
	v_sub_f32_e32 v185, v185, v224
	v_sub_f32_e32 v184, v184, v224
	v_sub_f32_e32 v187, v187, v224
	v_sub_f32_e32 v186, v186, v224
	v_pk_mul_f32 v[196:197], v[224:225], v[182:183] op_sel:[1,0]
	v_pk_mul_f32 v[198:199], v[224:225], v[180:181] op_sel:[1,0]
	v_pk_mul_f32 v[228:229], v[224:225], v[186:187] op_sel:[1,0]
	v_pk_mul_f32 v[224:225], v[224:225], v[184:185] op_sel:[1,0]
	v_pk_add_f32 v[184:185], v[206:207], 1.0 op_sel_hi:[1,0]
	v_pk_add_f32 v[186:187], v[204:205], 1.0 op_sel_hi:[1,0]
	v_pk_add_f32 v[180:181], v[210:211], 1.0 op_sel_hi:[1,0]
	v_pk_add_f32 v[182:183], v[208:209], 1.0 op_sel_hi:[1,0]
	v_pk_fma_f32 v[198:199], v[166:167], v[198:199], v[174:175]
	v_pk_fma_f32 v[196:197], v[162:163], v[196:197], v[170:171]
	v_pk_fma_f32 v[204:205], v[168:169], v[224:225], v[176:177]
	v_pk_fma_f32 v[206:207], v[164:165], v[228:229], v[172:173]
	v_sub_f32_e32 v201, v201, v226
	v_sub_f32_e32 v200, v200, v226
	v_sub_f32_e32 v203, v203, v226
	v_sub_f32_e32 v202, v202, v226
	v_pk_fma_f32 v[126:127], v[126:127], v[184:185], v[196:197]
	v_pk_fma_f32 v[124:125], v[124:125], v[186:187], v[198:199]
	v_pk_fma_f32 v[122:123], v[122:123], v[180:181], v[206:207]
	v_pk_fma_f32 v[120:121], v[120:121], v[182:183], v[204:205]
	global_store_dwordx4 v[150:151], v[124:127], off nt
	global_store_dwordx4 v[150:151], v[120:123], off offset:16 nt
	global_load_dwordx2 v[126:127], v[152:153], off
	v_add_co_u32_e32 v210, vcc, s61, v150
	v_pk_mul_f32 v[120:121], v[226:227], v[202:203] op_sel:[1,0]
	v_pk_mul_f32 v[122:123], v[226:227], v[200:201] op_sel:[1,0]
	v_pk_fma_f32 v[120:121], v[162:163], v[120:121], v[170:171]
	v_pk_fma_f32 v[122:123], v[166:167], v[122:123], v[174:175]
	v_pk_fma_f32 v[118:119], v[118:119], v[184:185], v[120:121]
	v_pk_fma_f32 v[116:117], v[116:117], v[186:187], v[122:123]
	global_store_dwordx4 v[148:149], v[116:119], off nt
	v_addc_co_u32_e32 v211, vcc, 0, v151, vcc
	s_nop 0
	v_sub_f32_e32 v117, v213, v226
	v_sub_f32_e32 v116, v212, v226
	v_sub_f32_e32 v119, v215, v226
	v_sub_f32_e32 v118, v214, v226
	v_pk_mul_f32 v[118:119], v[226:227], v[118:119] op_sel:[1,0]
	v_pk_mul_f32 v[116:117], v[226:227], v[116:117] op_sel:[1,0]
	v_pk_fma_f32 v[118:119], v[164:165], v[118:119], v[172:173]
	v_pk_fma_f32 v[116:117], v[168:169], v[116:117], v[176:177]
	v_pk_fma_f32 v[114:115], v[114:115], v[180:181], v[118:119]
	v_pk_fma_f32 v[112:113], v[112:113], v[182:183], v[116:117]
	global_store_dwordx4 v[148:149], v[112:115], off offset:16 nt
	s_and_b64 vcc, exec, s[4:5]
	s_waitcnt vmcnt(0)
	v_sub_f32_e32 v213, v221, v126
	v_or_b32_e32 v112, 48, v178
	v_ashrrev_i32_e32 v113, 31, v112
	v_lshl_add_u64 v[120:121], v[112:113], 3, s[24:25]
	v_lshlrev_b64 v[112:113], 12, v[112:113]
	v_lshl_add_u64 v[112:113], s[26:27], 0, v[112:113]
	global_load_dwordx2 v[208:209], v[120:121], off
	v_lshl_add_u64 v[116:117], v[112:113], 0, v[188:189]
	global_load_dwordx4 v[122:125], v[116:117], off
	global_load_dwordx4 v[196:199], v[116:117], off offset:16
	v_sub_f32_e32 v212, v220, v126
	v_sub_f32_e32 v215, v223, v126
	v_sub_f32_e32 v214, v222, v126
	v_sub_f32_e32 v217, v217, v126
	v_sub_f32_e32 v216, v216, v126
	v_sub_f32_e32 v219, v219, v126
	v_sub_f32_e32 v218, v218, v126
	v_pk_mul_f32 v[214:215], v[126:127], v[214:215] op_sel:[1,0]
	v_pk_mul_f32 v[212:213], v[126:127], v[212:213] op_sel:[1,0]
	v_pk_mul_f32 v[218:219], v[126:127], v[218:219] op_sel:[1,0]
	v_pk_mul_f32 v[126:127], v[126:127], v[216:217] op_sel:[1,0]
	v_pk_fma_f32 v[212:213], v[166:167], v[212:213], v[174:175]
	v_pk_fma_f32 v[214:215], v[162:163], v[214:215], v[170:171]
	v_pk_fma_f32 v[126:127], v[168:169], v[126:127], v[176:177]
	v_pk_fma_f32 v[216:217], v[164:165], v[218:219], v[172:173]
	v_pk_fma_f32 v[110:111], v[110:111], v[184:185], v[214:215]
	v_pk_fma_f32 v[108:109], v[108:109], v[186:187], v[212:213]
	v_add_u32_e32 v112, 0x90, v178
	v_lshl_add_u64 v[114:115], v[150:151], 0, s[0:1]
	global_load_dwordx4 v[200:203], v[210:211], off
	global_load_dwordx4 v[204:207], v[114:115], off offset:16
	v_pk_fma_f32 v[106:107], v[106:107], v[180:181], v[216:217]
	v_pk_fma_f32 v[104:105], v[104:105], v[182:183], v[126:127]
	global_store_dwordx4 v[146:147], v[108:111], off nt
	global_store_dwordx4 v[146:147], v[104:107], off offset:16 nt
	v_ashrrev_i32_e32 v113, 31, v112
	global_load_dwordx2 v[126:127], v[144:145], off offset:1024
	v_lshl_add_u64 v[118:119], v[112:113], 3, s[24:25]
	v_lshlrev_b64 v[112:113], 12, v[112:113]
	v_lshl_add_u64 v[112:113], s[26:27], 0, v[112:113]
	v_lshl_add_u64 v[112:113], v[112:113], 0, v[188:189]
	s_waitcnt vmcnt(0)
	v_sub_f32_e32 v123, v123, v208
	v_sub_f32_e32 v122, v122, v208
	v_sub_f32_e32 v125, v125, v208
	v_sub_f32_e32 v124, v124, v208
	v_sub_f32_e32 v197, v197, v208
	v_sub_f32_e32 v196, v196, v208
	v_sub_f32_e32 v199, v199, v208
	v_sub_f32_e32 v198, v198, v208
	v_pk_mul_f32 v[124:125], v[208:209], v[124:125] op_sel:[1,0]
	v_pk_mul_f32 v[122:123], v[208:209], v[122:123] op_sel:[1,0]
	v_pk_mul_f32 v[198:199], v[208:209], v[198:199] op_sel:[1,0]
	v_pk_mul_f32 v[196:197], v[208:209], v[196:197] op_sel:[1,0]
	v_pk_fma_f32 v[122:123], v[166:167], v[122:123], v[174:175]
	v_pk_fma_f32 v[104:105], v[162:163], v[124:125], v[170:171]
	v_pk_fma_f32 v[106:107], v[168:169], v[196:197], v[176:177]
	v_pk_fma_f32 v[108:109], v[164:165], v[198:199], v[172:173]
	v_pk_fma_f32 v[102:103], v[102:103], v[184:185], v[104:105]
	v_pk_fma_f32 v[100:101], v[100:101], v[186:187], v[122:123]
	v_pk_fma_f32 v[98:99], v[98:99], v[180:181], v[108:109]
	v_pk_fma_f32 v[96:97], v[96:97], v[182:183], v[106:107]
	global_store_dwordx4 v[116:117], v[100:103], off nt
	global_store_dwordx4 v[116:117], v[96:99], off offset:16 nt
	global_load_dwordx2 v[208:209], v[118:119], off
	global_load_dwordx4 v[104:107], v[112:113], off
	global_load_dwordx4 v[108:111], v[112:113], off offset:16
	v_add_u32_e32 v96, 0xa0, v178
	v_add_u32_e32 v98, 0xb0, v178
	v_ashrrev_i32_e32 v97, 31, v96
	v_ashrrev_i32_e32 v99, 31, v98
	v_lshl_add_u64 v[102:103], v[96:97], 3, s[24:25]
	v_lshlrev_b64 v[96:97], 12, v[96:97]
	v_lshl_add_u64 v[100:101], v[98:99], 3, s[24:25]
	v_lshlrev_b64 v[98:99], 12, v[98:99]
	v_lshl_add_u64 v[96:97], s[26:27], 0, v[96:97]
	v_lshl_add_u64 v[122:123], s[26:27], 0, v[98:99]
	v_lshl_add_u64 v[98:99], v[96:97], 0, v[188:189]
	v_lshl_add_u64 v[96:97], v[122:123], 0, v[188:189]
	v_sub_f32_e32 v179, v201, v126
	v_sub_f32_e32 v178, v200, v126
	v_sub_f32_e32 v189, v203, v126
	v_sub_f32_e32 v188, v202, v126
	v_sub_f32_e32 v203, v207, v126
	v_sub_f32_e32 v202, v206, v126
	v_sub_f32_e32 v201, v205, v126
	v_sub_f32_e32 v200, v204, v126
	v_pk_mul_f32 v[188:189], v[126:127], v[188:189] op_sel:[1,0]
	v_pk_mul_f32 v[178:179], v[126:127], v[178:179] op_sel:[1,0]
	v_pk_mul_f32 v[202:203], v[126:127], v[202:203] op_sel:[1,0]
	v_pk_mul_f32 v[126:127], v[126:127], v[200:201] op_sel:[1,0]
	v_pk_fma_f32 v[178:179], v[166:167], v[178:179], v[174:175]
	v_pk_fma_f32 v[188:189], v[162:163], v[188:189], v[170:171]
	v_pk_fma_f32 v[200:201], v[164:165], v[202:203], v[172:173]
	v_pk_fma_f32 v[126:127], v[168:169], v[126:127], v[176:177]
	v_pk_fma_f32 v[94:95], v[94:95], v[184:185], v[188:189]
	v_pk_fma_f32 v[92:93], v[92:93], v[186:187], v[178:179]
	v_pk_fma_f32 v[90:91], v[90:91], v[180:181], v[200:201]
	global_load_dwordx4 v[122:125], v[98:99], off offset:16
	global_load_dwordx4 v[196:199], v[98:99], off
	v_pk_fma_f32 v[88:89], v[88:89], v[182:183], v[126:127]
	global_store_dwordx4 v[210:211], v[92:95], off nt
	global_store_dwordx4 v[114:115], v[88:91], off offset:16 nt
	global_load_dwordx2 v[88:89], v[102:103], off
	s_waitcnt vmcnt(0)
	v_sub_f32_e32 v105, v105, v208
	v_sub_f32_e32 v104, v104, v208
	v_sub_f32_e32 v107, v107, v208
	v_sub_f32_e32 v106, v106, v208
	v_sub_f32_e32 v109, v109, v208
	v_sub_f32_e32 v108, v108, v208
	v_sub_f32_e32 v111, v111, v208
	v_sub_f32_e32 v110, v110, v208
	v_pk_mul_f32 v[106:107], v[208:209], v[106:107] op_sel:[1,0]
	v_pk_mul_f32 v[104:105], v[208:209], v[104:105] op_sel:[1,0]
	v_pk_mul_f32 v[110:111], v[208:209], v[110:111] op_sel:[1,0]
	v_pk_mul_f32 v[108:109], v[208:209], v[108:109] op_sel:[1,0]
	v_pk_fma_f32 v[104:105], v[166:167], v[104:105], v[174:175]
	v_pk_fma_f32 v[90:91], v[162:163], v[106:107], v[170:171]
	v_pk_fma_f32 v[92:93], v[168:169], v[108:109], v[176:177]
	v_pk_fma_f32 v[94:95], v[164:165], v[110:111], v[172:173]
	v_pk_fma_f32 v[86:87], v[86:87], v[184:185], v[90:91]
	v_pk_fma_f32 v[84:85], v[84:85], v[186:187], v[104:105]
	v_pk_fma_f32 v[82:83], v[82:83], v[180:181], v[94:95]
	v_pk_fma_f32 v[80:81], v[80:81], v[182:183], v[92:93]
	global_store_dwordx4 v[112:113], v[84:87], off nt
	global_store_dwordx4 v[112:113], v[80:83], off offset:16 nt
	global_load_dwordx2 v[90:91], v[100:101], off
	s_nop 0
	global_load_dwordx4 v[80:83], v[96:97], off
	global_load_dwordx4 v[84:87], v[96:97], off offset:16
	v_sub_f32_e32 v93, v197, v88
	v_sub_f32_e32 v92, v196, v88
	v_sub_f32_e32 v95, v199, v88
	v_sub_f32_e32 v94, v198, v88
	v_sub_f32_e32 v105, v123, v88
	v_sub_f32_e32 v104, v122, v88
	v_sub_f32_e32 v107, v125, v88
	v_sub_f32_e32 v106, v124, v88
	v_pk_mul_f32 v[94:95], v[88:89], v[94:95] op_sel:[1,0]
	v_pk_mul_f32 v[92:93], v[88:89], v[92:93] op_sel:[1,0]
	v_pk_mul_f32 v[106:107], v[88:89], v[106:107] op_sel:[1,0]
	v_pk_mul_f32 v[88:89], v[88:89], v[104:105] op_sel:[1,0]
	v_pk_fma_f32 v[92:93], v[166:167], v[92:93], v[174:175]
	v_pk_fma_f32 v[94:95], v[162:163], v[94:95], v[170:171]
	v_pk_fma_f32 v[88:89], v[168:169], v[88:89], v[176:177]
	v_pk_fma_f32 v[104:105], v[164:165], v[106:107], v[172:173]
	v_pk_fma_f32 v[78:79], v[78:79], v[184:185], v[94:95]
	v_pk_fma_f32 v[76:77], v[76:77], v[186:187], v[92:93]
	v_pk_fma_f32 v[74:75], v[74:75], v[180:181], v[104:105]
	v_pk_fma_f32 v[72:73], v[72:73], v[182:183], v[88:89]
	global_store_dwordx4 v[98:99], v[76:79], off nt
	global_store_dwordx4 v[98:99], v[72:75], off offset:16 nt
	s_waitcnt vmcnt(0)
	v_sub_f32_e32 v81, v81, v90
	v_sub_f32_e32 v80, v80, v90
	v_sub_f32_e32 v83, v83, v90
	v_sub_f32_e32 v82, v82, v90
	v_sub_f32_e32 v85, v85, v90
	v_sub_f32_e32 v84, v84, v90
	v_sub_f32_e32 v87, v87, v90
	v_sub_f32_e32 v86, v86, v90
	v_pk_mul_f32 v[82:83], v[90:91], v[82:83] op_sel:[1,0]
	v_pk_mul_f32 v[80:81], v[90:91], v[80:81] op_sel:[1,0]
	v_pk_mul_f32 v[86:87], v[90:91], v[86:87] op_sel:[1,0]
	v_pk_mul_f32 v[84:85], v[90:91], v[84:85] op_sel:[1,0]
	v_pk_fma_f32 v[80:81], v[166:167], v[80:81], v[174:175]
	v_pk_fma_f32 v[82:83], v[162:163], v[82:83], v[170:171]
	v_pk_fma_f32 v[84:85], v[168:169], v[84:85], v[176:177]
	v_pk_fma_f32 v[86:87], v[164:165], v[86:87], v[172:173]
	v_pk_fma_f32 v[70:71], v[70:71], v[184:185], v[82:83]
	v_pk_fma_f32 v[68:69], v[68:69], v[186:187], v[80:81]
	v_pk_fma_f32 v[66:67], v[66:67], v[180:181], v[86:87]
	v_pk_fma_f32 v[64:65], v[64:65], v[182:183], v[84:85]
	global_store_dwordx4 v[96:97], v[68:71], off nt
	global_store_dwordx4 v[96:97], v[64:67], off offset:16 nt
	global_load_dwordx4 v[66:69], v[160:161], off offset:512
	s_nop 0
	global_load_dwordx4 v[70:73], v[160:161], off offset:528
	global_load_dwordx4 v[74:77], v[154:155], off offset:512
	global_load_dwordx4 v[78:81], v[154:155], off offset:528
	global_load_dwordx4 v[82:85], v[156:157], off offset:512
	global_load_dwordx4 v[86:89], v[156:157], off offset:528
	global_load_dwordx2 v[94:95], v[144:145], off
	global_load_dwordx4 v[90:93], v[150:151], off offset:512
	global_load_dwordx4 v[104:107], v[150:151], off offset:528
	global_load_dwordx2 v[126:127], v[158:159], off
	global_load_dwordx4 v[108:111], v[148:149], off offset:512
	global_load_dwordx4 v[122:125], v[148:149], off offset:528
	global_load_dwordx4 v[154:157], v[146:147], off offset:528
	global_load_dwordx4 v[158:161], v[146:147], off offset:512
	s_waitcnt vmcnt(0)
	v_pk_add_f32 v[64:65], v[68:69], 1.0 op_sel_hi:[1,0]
	v_pk_add_f32 v[68:69], v[72:73], 1.0 op_sel_hi:[1,0]
	v_pk_mul_f32 v[72:73], v[76:77], s[8:9] op_sel_hi:[1,0]
	v_pk_mul_f32 v[76:77], v[74:75], s[8:9] op_sel_hi:[1,0]
	v_pk_mul_f32 v[74:75], v[80:81], s[8:9] op_sel_hi:[1,0]
	v_pk_mul_f32 v[80:81], v[84:85], s[8:9] op_sel_hi:[1,0]
	v_pk_mul_f32 v[84:85], v[82:83], s[8:9] op_sel_hi:[1,0]
	v_pk_mul_f32 v[82:83], v[88:89], s[8:9] op_sel_hi:[1,0]
	v_sub_f32_e32 v89, v91, v94
	v_sub_f32_e32 v88, v90, v94
	v_sub_f32_e32 v91, v93, v94
	v_sub_f32_e32 v90, v92, v94
	v_sub_f32_e32 v93, v105, v94
	v_sub_f32_e32 v92, v104, v94
	v_sub_f32_e32 v105, v107, v94
	v_sub_f32_e32 v104, v106, v94
	v_pk_mul_f32 v[90:91], v[94:95], v[90:91] op_sel:[1,0]
	v_pk_mul_f32 v[88:89], v[94:95], v[88:89] op_sel:[1,0]
	v_pk_add_f32 v[66:67], v[66:67], 1.0 op_sel_hi:[1,0]
	v_pk_mul_f32 v[78:79], v[78:79], s[8:9] op_sel_hi:[1,0]
	v_pk_mul_f32 v[86:87], v[86:87], s[8:9] op_sel_hi:[1,0]
	v_pk_mul_f32 v[104:105], v[94:95], v[104:105] op_sel:[1,0]
	v_pk_mul_f32 v[92:93], v[94:95], v[92:93] op_sel:[1,0]
	v_pk_fma_f32 v[88:89], v[76:77], v[88:89], v[84:85]
	v_pk_fma_f32 v[90:91], v[72:73], v[90:91], v[80:81]
	v_pk_add_f32 v[70:71], v[70:71], 1.0 op_sel_hi:[1,0]
	v_pk_fma_f32 v[92:93], v[78:79], v[92:93], v[86:87]
	v_pk_fma_f32 v[104:105], v[74:75], v[104:105], v[82:83]
	v_pk_fma_f32 v[62:63], v[62:63], v[64:65], v[90:91]
	v_pk_fma_f32 v[60:61], v[60:61], v[66:67], v[88:89]
	v_pk_fma_f32 v[58:59], v[58:59], v[68:69], v[104:105]
	v_pk_fma_f32 v[56:57], v[56:57], v[70:71], v[92:93]
	global_store_dwordx4 v[150:151], v[60:63], off offset:512 nt
	global_store_dwordx4 v[150:151], v[56:59], off offset:528 nt
	global_load_dwordx2 v[88:89], v[152:153], off
	v_sub_f32_e32 v107, v109, v126
	v_sub_f32_e32 v106, v108, v126
	v_sub_f32_e32 v109, v111, v126
	v_sub_f32_e32 v108, v110, v126
	v_sub_f32_e32 v111, v123, v126
	v_sub_f32_e32 v110, v122, v126
	v_sub_f32_e32 v123, v125, v126
	v_sub_f32_e32 v122, v124, v126
	v_pk_mul_f32 v[94:95], v[126:127], v[108:109] op_sel:[1,0]
	v_pk_mul_f32 v[106:107], v[126:127], v[106:107] op_sel:[1,0]
	v_pk_mul_f32 v[108:109], v[126:127], v[122:123] op_sel:[1,0]
	v_pk_mul_f32 v[110:111], v[126:127], v[110:111] op_sel:[1,0]
	v_pk_fma_f32 v[106:107], v[76:77], v[106:107], v[84:85]
	v_pk_fma_f32 v[56:57], v[72:73], v[94:95], v[80:81]
	v_pk_fma_f32 v[58:59], v[78:79], v[110:111], v[86:87]
	v_pk_fma_f32 v[60:61], v[74:75], v[108:109], v[82:83]
	v_pk_fma_f32 v[54:55], v[54:55], v[64:65], v[56:57]
	v_pk_fma_f32 v[52:53], v[52:53], v[66:67], v[106:107]
	v_pk_fma_f32 v[50:51], v[50:51], v[68:69], v[60:61]
	v_pk_fma_f32 v[48:49], v[48:49], v[70:71], v[58:59]
	global_store_dwordx4 v[148:149], v[52:55], off offset:512 nt
	global_store_dwordx4 v[148:149], v[48:51], off offset:528 nt
	global_load_dwordx2 v[90:91], v[120:121], off
	s_nop 0
	global_load_dwordx4 v[48:51], v[116:117], off offset:512
	global_load_dwordx4 v[52:55], v[116:117], off offset:528
	global_load_dwordx4 v[56:59], v[114:115], off offset:528
	global_load_dwordx4 v[60:63], v[114:115], off offset:512
	s_waitcnt vmcnt(0)
	v_sub_f32_e32 v93, v159, v88
	v_sub_f32_e32 v92, v158, v88
	v_sub_f32_e32 v95, v161, v88
	v_sub_f32_e32 v94, v160, v88
	v_sub_f32_e32 v105, v155, v88
	v_sub_f32_e32 v104, v154, v88
	v_sub_f32_e32 v107, v157, v88
	v_sub_f32_e32 v106, v156, v88
	v_pk_mul_f32 v[94:95], v[88:89], v[94:95] op_sel:[1,0]
	v_pk_mul_f32 v[92:93], v[88:89], v[92:93] op_sel:[1,0]
	v_pk_mul_f32 v[106:107], v[88:89], v[106:107] op_sel:[1,0]
	v_pk_mul_f32 v[88:89], v[88:89], v[104:105] op_sel:[1,0]
	v_pk_fma_f32 v[92:93], v[76:77], v[92:93], v[84:85]
	v_pk_fma_f32 v[94:95], v[72:73], v[94:95], v[80:81]
	v_pk_fma_f32 v[88:89], v[78:79], v[88:89], v[86:87]
	v_pk_fma_f32 v[104:105], v[74:75], v[106:107], v[82:83]
	v_pk_fma_f32 v[46:47], v[46:47], v[64:65], v[94:95]
	v_pk_fma_f32 v[44:45], v[44:45], v[66:67], v[92:93]
	v_pk_fma_f32 v[42:43], v[42:43], v[68:69], v[104:105]
	v_pk_fma_f32 v[40:41], v[40:41], v[70:71], v[88:89]
	global_store_dwordx4 v[146:147], v[44:47], off offset:512 nt
	global_store_dwordx4 v[146:147], v[40:43], off offset:528 nt
	global_load_dwordx2 v[88:89], v[144:145], off offset:1024
	v_sub_f32_e32 v49, v49, v90
	v_sub_f32_e32 v48, v48, v90
	v_sub_f32_e32 v51, v51, v90
	v_sub_f32_e32 v50, v50, v90
	v_sub_f32_e32 v53, v53, v90
	v_sub_f32_e32 v52, v52, v90
	v_sub_f32_e32 v55, v55, v90
	v_sub_f32_e32 v54, v54, v90
	v_pk_mul_f32 v[50:51], v[90:91], v[50:51] op_sel:[1,0]
	v_pk_mul_f32 v[48:49], v[90:91], v[48:49] op_sel:[1,0]
	v_pk_mul_f32 v[54:55], v[90:91], v[54:55] op_sel:[1,0]
	v_pk_mul_f32 v[52:53], v[90:91], v[52:53] op_sel:[1,0]
	v_pk_fma_f32 v[48:49], v[76:77], v[48:49], v[84:85]
	v_pk_fma_f32 v[40:41], v[72:73], v[50:51], v[80:81]
	v_pk_fma_f32 v[42:43], v[78:79], v[52:53], v[86:87]
	v_pk_fma_f32 v[44:45], v[74:75], v[54:55], v[82:83]
	v_pk_fma_f32 v[38:39], v[38:39], v[64:65], v[40:41]
	v_pk_fma_f32 v[36:37], v[36:37], v[66:67], v[48:49]
	v_pk_fma_f32 v[34:35], v[34:35], v[68:69], v[44:45]
	v_pk_fma_f32 v[32:33], v[32:33], v[70:71], v[42:43]
	global_store_dwordx4 v[116:117], v[36:39], off offset:512 nt
	global_store_dwordx4 v[116:117], v[32:35], off offset:528 nt
	global_load_dwordx2 v[48:49], v[118:119], off
	s_nop 0
	global_load_dwordx4 v[32:35], v[112:113], off offset:512
	global_load_dwordx4 v[36:39], v[112:113], off offset:528
	global_load_dwordx4 v[40:43], v[98:99], off offset:528
	global_load_dwordx4 v[44:47], v[98:99], off offset:512
	s_waitcnt vmcnt(0)
	v_sub_f32_e32 v51, v61, v88
	v_sub_f32_e32 v50, v60, v88
	v_sub_f32_e32 v53, v63, v88
	v_sub_f32_e32 v52, v62, v88
	v_sub_f32_e32 v55, v57, v88
	v_sub_f32_e32 v54, v56, v88
	v_sub_f32_e32 v57, v59, v88
	v_sub_f32_e32 v56, v58, v88
	v_pk_mul_f32 v[52:53], v[88:89], v[52:53] op_sel:[1,0]
	v_pk_mul_f32 v[50:51], v[88:89], v[50:51] op_sel:[1,0]
	v_pk_mul_f32 v[56:57], v[88:89], v[56:57] op_sel:[1,0]
	v_pk_mul_f32 v[54:55], v[88:89], v[54:55] op_sel:[1,0]
	v_pk_fma_f32 v[50:51], v[76:77], v[50:51], v[84:85]
	v_pk_fma_f32 v[52:53], v[72:73], v[52:53], v[80:81]
	v_pk_fma_f32 v[54:55], v[78:79], v[54:55], v[86:87]
	v_pk_fma_f32 v[56:57], v[74:75], v[56:57], v[82:83]
	v_pk_fma_f32 v[30:31], v[30:31], v[64:65], v[52:53]
	v_pk_fma_f32 v[28:29], v[28:29], v[66:67], v[50:51]
	v_pk_fma_f32 v[26:27], v[26:27], v[68:69], v[56:57]
	v_pk_fma_f32 v[24:25], v[24:25], v[70:71], v[54:55]
	global_store_dwordx4 v[114:115], v[28:31], off offset:512 nt
	global_store_dwordx4 v[114:115], v[24:27], off offset:528 nt
	global_load_dwordx2 v[24:25], v[102:103], off
	v_sub_f32_e32 v33, v33, v48
	v_sub_f32_e32 v32, v32, v48
	v_sub_f32_e32 v35, v35, v48
	v_sub_f32_e32 v34, v34, v48
	v_sub_f32_e32 v37, v37, v48
	v_sub_f32_e32 v36, v36, v48
	v_sub_f32_e32 v39, v39, v48
	v_sub_f32_e32 v38, v38, v48
	v_pk_mul_f32 v[34:35], v[48:49], v[34:35] op_sel:[1,0]
	v_pk_mul_f32 v[32:33], v[48:49], v[32:33] op_sel:[1,0]
	v_pk_mul_f32 v[38:39], v[48:49], v[38:39] op_sel:[1,0]
	v_pk_mul_f32 v[36:37], v[48:49], v[36:37] op_sel:[1,0]
	v_pk_fma_f32 v[32:33], v[76:77], v[32:33], v[84:85]
	v_pk_fma_f32 v[26:27], v[72:73], v[34:35], v[80:81]
	v_pk_fma_f32 v[28:29], v[78:79], v[36:37], v[86:87]
	v_pk_fma_f32 v[30:31], v[74:75], v[38:39], v[82:83]
	v_pk_fma_f32 v[22:23], v[22:23], v[64:65], v[26:27]
	v_pk_fma_f32 v[20:21], v[20:21], v[66:67], v[32:33]
	v_pk_fma_f32 v[18:19], v[18:19], v[68:69], v[30:31]
	v_pk_fma_f32 v[16:17], v[16:17], v[70:71], v[28:29]
	global_store_dwordx4 v[112:113], v[20:23], off offset:512 nt
	global_store_dwordx4 v[112:113], v[16:19], off offset:528 nt
	global_load_dwordx2 v[26:27], v[100:101], off
	s_nop 0
	global_load_dwordx4 v[16:19], v[96:97], off offset:512
	global_load_dwordx4 v[20:23], v[96:97], off offset:528
	s_waitcnt vmcnt(0)
	v_sub_f32_e32 v29, v45, v24
	v_sub_f32_e32 v28, v44, v24
	v_sub_f32_e32 v31, v47, v24
	v_sub_f32_e32 v30, v46, v24
	v_sub_f32_e32 v33, v41, v24
	v_sub_f32_e32 v32, v40, v24
	v_sub_f32_e32 v35, v43, v24
	v_sub_f32_e32 v34, v42, v24
	v_pk_mul_f32 v[30:31], v[24:25], v[30:31] op_sel:[1,0]
	v_pk_mul_f32 v[28:29], v[24:25], v[28:29] op_sel:[1,0]
	v_pk_mul_f32 v[34:35], v[24:25], v[34:35] op_sel:[1,0]
	v_pk_mul_f32 v[24:25], v[24:25], v[32:33] op_sel:[1,0]
	v_pk_fma_f32 v[28:29], v[76:77], v[28:29], v[84:85]
	v_pk_fma_f32 v[30:31], v[72:73], v[30:31], v[80:81]
	v_pk_fma_f32 v[24:25], v[78:79], v[24:25], v[86:87]
	v_pk_fma_f32 v[32:33], v[74:75], v[34:35], v[82:83]
	v_pk_fma_f32 v[14:15], v[14:15], v[64:65], v[30:31]
	v_pk_fma_f32 v[12:13], v[12:13], v[66:67], v[28:29]
	v_pk_fma_f32 v[10:11], v[10:11], v[68:69], v[32:33]
	v_pk_fma_f32 v[8:9], v[8:9], v[70:71], v[24:25]
	global_store_dwordx4 v[98:99], v[12:15], off offset:512 nt
	global_store_dwordx4 v[98:99], v[8:11], off offset:528 nt
	v_sub_f32_e32 v17, v17, v26
	v_sub_f32_e32 v16, v16, v26
	v_sub_f32_e32 v19, v19, v26
	v_sub_f32_e32 v18, v18, v26
	v_sub_f32_e32 v21, v21, v26
	v_sub_f32_e32 v20, v20, v26
	v_sub_f32_e32 v23, v23, v26
	v_sub_f32_e32 v22, v22, v26
	v_pk_mul_f32 v[18:19], v[26:27], v[18:19] op_sel:[1,0]
	v_pk_mul_f32 v[16:17], v[26:27], v[16:17] op_sel:[1,0]
	v_pk_mul_f32 v[22:23], v[26:27], v[22:23] op_sel:[1,0]
	v_pk_mul_f32 v[20:21], v[26:27], v[20:21] op_sel:[1,0]
	v_pk_fma_f32 v[16:17], v[76:77], v[16:17], v[84:85]
	v_pk_fma_f32 v[18:19], v[72:73], v[18:19], v[80:81]
	v_pk_fma_f32 v[20:21], v[78:79], v[20:21], v[86:87]
	v_pk_fma_f32 v[22:23], v[74:75], v[22:23], v[82:83]
	v_pk_fma_f32 v[6:7], v[6:7], v[64:65], v[18:19]
	v_pk_fma_f32 v[4:5], v[4:5], v[66:67], v[16:17]
	v_pk_fma_f32 v[2:3], v[2:3], v[68:69], v[22:23]
	v_pk_fma_f32 v[0:1], v[0:1], v[70:71], v[20:21]
	global_store_dwordx4 v[96:97], v[4:7], off offset:512 nt
	global_store_dwordx4 v[96:97], v[0:3], off offset:528 nt
	s_cbranch_vccz .LBB0_958
	s_waitcnt vmcnt(0)
	s_cmpk_gt_u32 s3, 0xff
	s_cbranch_scc1 .LBB0_969
	s_barrier
